# variant: each relocated DMA piece split over two adjacent PV gaps (address/m0 prep in one, issue in the next)
# baseline (speedup 1.0000x reference)
.LBB0_463:
	s_mov_b32 s8, s60
	s_mov_b32 s9, s16
	s_mov_b32 s10, s59
	ds_read_b128 v[4:7], v219 offset:1024
	v_lshl_add_u32 v207, s11, 14, v214
	v_add_f32_e32 v2, v100, v101
	v_add_f32_e32 v2, v102, v2
	v_add_f32_e32 v2, v103, v2
	v_add_f32_e32 v2, v104, v2
	v_add_f32_e32 v2, v105, v2
	v_cvt_pk_bf16_f32 v160, v100, v101
	v_cvt_pk_bf16_f32 v161, v102, v103
	s_waitcnt lgkmcnt(1)
	v_mfma_f32_32x32x16_bf16 v[132:147], v[192:195], v[116:119], 0
	v_mfma_f32_32x32x16_bf16 v[116:131], v[184:187], v[116:119], 0
	v_add_f32_e32 v2, v106, v2
	v_add_f32_e32 v2, v107, v2
	v_add_f32_e32 v2, v108, v2
	v_add_f32_e32 v2, v109, v2
	v_cvt_pk_bf16_f32 v162, v104, v105
	v_cvt_pk_bf16_f32 v163, v106, v107
	ds_read_b128 v[10:13], v219 offset:2048
	ds_read_b64_tr_b16 v[14:15], v207 offset:24576
	ds_read_b64_tr_b16 v[16:17], v207 offset:25088
	v_add_f32_e32 v2, v110, v2
	v_add_f32_e32 v2, v111, v2
	v_add_f32_e32 v2, v112, v2
	v_add_f32_e32 v2, v113, v2
	v_cvt_pk_bf16_f32 v156, v108, v109
	v_cvt_pk_bf16_f32 v157, v110, v111
	s_waitcnt lgkmcnt(3)
	v_mfma_f32_32x32x16_bf16 v[132:147], v[188:191], v[4:7], v[132:147]
	v_mfma_f32_32x32x16_bf16 v[116:131], v[180:183], v[4:7], v[116:131]
	v_add_f32_e32 v2, v114, v2
	v_add_f32_e32 v2, v115, v2
	v_add_f32_e32 v2, v84, v2
	v_add_f32_e32 v2, v85, v2
	v_cvt_pk_bf16_f32 v158, v112, v113
	v_cvt_pk_bf16_f32 v159, v114, v115
	ds_read_b128 v[4:7], v219 offset:3072
	ds_read_b64_tr_b16 v[100:101], v207 offset:28672
	ds_read_b64_tr_b16 v[102:103], v207 offset:29184
	v_add_f32_e32 v2, v86, v2
	v_add_f32_e32 v2, v87, v2
	v_add_f32_e32 v2, v88, v2
	v_add_f32_e32 v2, v89, v2
	v_cvt_pk_bf16_f32 v152, v84, v85
	v_cvt_pk_bf16_f32 v153, v86, v87
	s_waitcnt lgkmcnt(5)
	v_mfma_f32_32x32x16_bf16 v[132:147], v[176:179], v[10:13], v[132:147]
	v_mfma_f32_32x32x16_bf16 v[116:131], v[172:175], v[10:13], v[116:131]
	v_add_f32_e32 v2, v90, v2
	v_add_f32_e32 v2, v91, v2
	v_add_f32_e32 v2, v92, v2
	v_add_f32_e32 v2, v93, v2
	v_cvt_pk_bf16_f32 v154, v88, v89
	v_cvt_pk_bf16_f32 v155, v90, v91
	ds_read_b64_tr_b16 v[84:85], v207 offset:25600
	ds_read_b64_tr_b16 v[86:87], v207 offset:26112
	v_add_f32_e32 v2, v94, v2
	v_add_f32_e32 v2, v95, v2
	v_add_f32_e32 v2, v96, v2
	v_add_f32_e32 v2, v97, v2
	v_cvt_pk_bf16_f32 v148, v92, v93
	v_cvt_pk_bf16_f32 v149, v94, v95
	s_waitcnt lgkmcnt(4)
	v_mfma_f32_32x32x16_bf16 v[132:147], v[168:171], v[4:7], v[132:147]
	v_mfma_f32_32x32x16_bf16 v[116:131], v[164:167], v[4:7], v[116:131]
	v_add_f32_e32 v2, v98, v2
	v_add_f32_e32 v2, v99, v2
	v_cvt_pk_bf16_f32 v150, v96, v97
	v_cvt_pk_bf16_f32 v151, v98, v99
	v_add_f32_e32 v2, v225, v2
	ds_read_b64_tr_b16 v[4:5], v207 offset:29696
	ds_read_b64_tr_b16 v[6:7], v207 offset:30208
	v_mfma_f32_32x32x16_bf16 v[68:83], v[160:163], v[14:17], v[68:83]
	v_exp_f32_e32 v132, v132
	v_exp_f32_e32 v133, v133
	s_add_u32 s98, s6, s28
	s_addc_u32 s99, s7, s29
	v_lshl_add_u64 v[254:255], v[204:205], 0, s[98:99]
	s_lshl_b32 s100, s59, 13
	s_add_i32 s100, s100, s49
	ds_read_b64_tr_b16 v[14:15], v207 offset:26624
	ds_read_b64_tr_b16 v[16:17], v207 offset:27136
	s_waitcnt lgkmcnt(6)
	v_mfma_f32_32x32x16_bf16 v[52:67], v[160:163], v[100:103], v[52:67]
	v_exp_f32_e32 v134, v134
	v_exp_f32_e32 v135, v135
	s_mov_b32 m0, s100
	s_nop 0
	global_load_lds_dwordx4 v[254:255], off
	ds_read_b64_tr_b16 v[88:89], v207 offset:30720
	ds_read_b64_tr_b16 v[90:91], v207 offset:31232
	s_waitcnt lgkmcnt(6)
	v_mfma_f32_32x32x16_bf16 v[68:83], v[156:159], v[84:87], v[68:83]
	v_exp_f32_e32 v136, v136
	v_exp_f32_e32 v137, v137
	ds_read_b64_tr_b16 v[84:85], v207 offset:27648
	ds_read_b64_tr_b16 v[86:87], v207 offset:28160
	s_waitcnt lgkmcnt(6)
	v_mfma_f32_32x32x16_bf16 v[52:67], v[156:159], v[4:7], v[52:67]
	v_exp_f32_e32 v138, v138
	v_exp_f32_e32 v139, v139
	s_add_u32 s98, s6, s30
	s_addc_u32 s99, s7, s31
	v_lshl_add_u64 v[254:255], v[8:9], 0, s[98:99]
	s_lshl_b32 s100, s60, 14
	s_add_i32 s100, s100, s58
	ds_read_b64_tr_b16 v[4:5], v207 offset:31744
	ds_read_b64_tr_b16 v[6:7], v207 offset:32256
	s_waitcnt lgkmcnt(6)
	v_mfma_f32_32x32x16_bf16 v[68:83], v[152:155], v[14:17], v[68:83]
	v_exp_f32_e32 v140, v140
	v_exp_f32_e32 v141, v141
	s_mov_b32 m0, s100
	s_nop 0
	global_load_lds_dwordx4 v[254:255], off
	ds_read_b64_tr_b16 v[14:15], v207 offset:32768
	ds_read_b64_tr_b16 v[16:17], v207 offset:33280
	s_waitcnt lgkmcnt(6)
	v_mfma_f32_32x32x16_bf16 v[52:67], v[152:155], v[88:91], v[52:67]
	v_exp_f32_e32 v142, v142
	v_exp_f32_e32 v143, v143
	ds_read_b64_tr_b16 v[88:89], v207 offset:36864
	ds_read_b64_tr_b16 v[90:91], v207 offset:37376
	s_waitcnt lgkmcnt(6)
	v_mfma_f32_32x32x16_bf16 v[68:83], v[148:151], v[84:87], v[68:83]
	v_exp_f32_e32 v144, v144
	v_exp_f32_e32 v145, v145
	ds_read_b64_tr_b16 v[84:85], v207 offset:33792
	ds_read_b64_tr_b16 v[86:87], v207 offset:34304
	s_waitcnt lgkmcnt(6)
	v_mfma_f32_32x32x16_bf16 v[52:67], v[148:151], v[4:7], v[52:67]
	v_exp_f32_e32 v146, v146
	v_exp_f32_e32 v147, v147
	ds_read_b64_tr_b16 v[92:93], v207 offset:37888
	ds_read_b64_tr_b16 v[94:95], v207 offset:38400
	s_lshl_b32 s11, s60, 13
	v_add_u32_e32 v4, s11, v222
	ds_read_b128 v[96:99], v4
	ds_read_b128 v[164:167], v4 offset:512
	s_waitcnt lgkmcnt(8)
	v_mfma_f32_32x32x16_bf16 v[36:51], v[160:163], v[14:17], v[36:51]
	v_exp_f32_e32 v116, v116
	v_exp_f32_e32 v117, v117
	ds_read_b64_tr_b16 v[14:15], v207 offset:34816
	ds_read_b64_tr_b16 v[16:17], v207 offset:35328
	ds_read_b128 v[168:171], v4 offset:2048
	ds_read_b128 v[172:175], v4 offset:2560
	s_waitcnt lgkmcnt(10)
	v_mfma_f32_32x32x16_bf16 v[20:35], v[160:163], v[88:91], v[20:35]
	v_exp_f32_e32 v118, v118
	v_exp_f32_e32 v119, v119
	ds_read_b64_tr_b16 v[88:89], v207 offset:38912
	ds_read_b64_tr_b16 v[90:91], v207 offset:39424
	ds_read_b128 v[176:179], v4 offset:4096
	ds_read_b128 v[180:183], v4 offset:4608
	s_waitcnt lgkmcnt(12)
	v_mfma_f32_32x32x16_bf16 v[36:51], v[156:159], v[84:87], v[36:51]
	v_exp_f32_e32 v120, v120
	v_exp_f32_e32 v121, v121
	ds_read_b64_tr_b16 v[84:85], v207 offset:35840
	ds_read_b64_tr_b16 v[86:87], v207 offset:36352
	ds_read_b128 v[184:187], v4 offset:6144
	ds_read_b128 v[4:7], v4 offset:6656
	s_waitcnt lgkmcnt(14)
	v_mfma_f32_32x32x16_bf16 v[20:35], v[156:159], v[92:95], v[20:35]
	v_exp_f32_e32 v122, v122
	v_exp_f32_e32 v123, v123
	ds_read_b64_tr_b16 v[92:93], v207 offset:39936
	ds_read_b64_tr_b16 v[94:95], v207 offset:40448
	s_waitcnt lgkmcnt(12)
	v_mfma_f32_32x32x16_bf16 v[36:51], v[152:155], v[14:17], v[36:51]
	v_exp_f32_e32 v124, v124
	v_exp_f32_e32 v125, v125
	s_add_u32 s98, s6, s34
	s_addc_u32 s99, s7, s35
	v_lshl_add_u64 v[254:255], v[8:9], 0, s[98:99]
	s_lshl_b32 s100, s60, 14
	s_add_i32 s100, s100, s58
	s_addk_i32 s100, 0x2000
	ds_read_b128 v[14:17], v219
	s_waitcnt lgkmcnt(9)
	v_mfma_f32_32x32x16_bf16 v[20:35], v[152:155], v[88:91], v[20:35]
	v_exp_f32_e32 v126, v126
	v_exp_f32_e32 v127, v127
	s_mov_b32 m0, s100
	s_nop 0
	global_load_lds_dwordx4 v[254:255], off
	s_waitcnt lgkmcnt(5)
	v_mfma_f32_32x32x16_bf16 v[36:51], v[148:151], v[84:87], v[36:51]
	v_exp_f32_e32 v128, v128
	v_exp_f32_e32 v129, v129
	s_waitcnt lgkmcnt(1)
	v_mfma_f32_32x32x16_bf16 v[20:35], v[148:151], v[92:95], v[20:35]
	v_exp_f32_e32 v130, v130
	v_exp_f32_e32 v131, v131
	s_waitcnt vmcnt(3) lgkmcnt(0)
	s_barrier
	s_add_i32 s16, s60, 1
	s_cmp_lg_u32 s60, 2
	s_cselect_b32 s59, s16, 0
	ds_read_b128 v[188:191], v219 offset:1024
	v_lshl_add_u32 v207, s10, 14, v214
	s_waitcnt lgkmcnt(1)
	v_mfma_f32_32x32x16_bf16 v[100:115], v[96:99], v[14:17], 0
	v_add_f32_e32 v84, v132, v133
	v_add_f32_e32 v84, v134, v84
	v_add_f32_e32 v84, v135, v84
	v_add_f32_e32 v84, v136, v84
	v_add_f32_e32 v84, v137, v84
	v_cvt_pk_bf16_f32 v160, v132, v133
	v_cvt_pk_bf16_f32 v161, v134, v135
	s_nop 0
	v_add_f32_e32 v84, v138, v84
	v_add_f32_e32 v84, v139, v84
	v_add_f32_e32 v84, v140, v84
	v_add_f32_e32 v148, v141, v84
	v_mfma_f32_32x32x16_bf16 v[84:99], v[164:167], v[14:17], 0
	v_cvt_pk_bf16_f32 v162, v136, v137
	v_cvt_pk_bf16_f32 v163, v138, v139
	ds_read_b128 v[14:17], v219 offset:2048
	ds_read_b64_tr_b16 v[132:133], v207 offset:24576
	ds_read_b64_tr_b16 v[134:135], v207 offset:25088
	s_waitcnt lgkmcnt(3)
	v_mfma_f32_32x32x16_bf16 v[100:115], v[168:171], v[188:191], v[100:115]
	v_add_f32_e32 v136, v142, v148
	v_add_f32_e32 v136, v143, v136
	v_add_f32_e32 v136, v144, v136
	v_add_f32_e32 v136, v145, v136
	v_cvt_pk_bf16_f32 v156, v140, v141
	v_cvt_pk_bf16_f32 v157, v142, v143
	v_mfma_f32_32x32x16_bf16 v[84:99], v[172:175], v[188:191], v[84:99]
	v_add_f32_e32 v136, v146, v136
	v_add_f32_e32 v136, v147, v136
	v_add_f32_e32 v136, v116, v136
	v_add_f32_e32 v148, v117, v136
	v_cvt_pk_bf16_f32 v158, v144, v145
	v_cvt_pk_bf16_f32 v159, v146, v147
	ds_read_b128 v[136:139], v219 offset:3072
	ds_read_b64_tr_b16 v[140:141], v207 offset:28672
	ds_read_b64_tr_b16 v[142:143], v207 offset:29184
	s_waitcnt lgkmcnt(5)
	v_mfma_f32_32x32x16_bf16 v[100:115], v[176:179], v[14:17], v[100:115]
	v_add_f32_e32 v144, v118, v148
	v_add_f32_e32 v144, v119, v144
	v_add_f32_e32 v144, v120, v144
	v_add_f32_e32 v144, v121, v144
	v_cvt_pk_bf16_f32 v152, v116, v117
	v_cvt_pk_bf16_f32 v153, v118, v119
	v_mfma_f32_32x32x16_bf16 v[84:99], v[180:183], v[14:17], v[84:99]
	v_add_f32_e32 v14, v122, v144
	v_add_f32_e32 v14, v123, v14
	v_add_f32_e32 v14, v124, v14
	v_add_f32_e32 v116, v125, v14
	v_cvt_pk_bf16_f32 v154, v120, v121
	v_cvt_pk_bf16_f32 v155, v122, v123
	ds_read_b64_tr_b16 v[14:15], v207 offset:25600
	ds_read_b64_tr_b16 v[16:17], v207 offset:26112
	s_waitcnt lgkmcnt(4)
	v_mfma_f32_32x32x16_bf16 v[100:115], v[184:187], v[136:139], v[100:115]
	v_add_f32_e32 v116, v126, v116
	v_add_f32_e32 v116, v127, v116
	v_add_f32_e32 v116, v128, v116
	v_add_f32_e32 v116, v129, v116
	v_cvt_pk_bf16_f32 v148, v124, v125
	v_cvt_pk_bf16_f32 v149, v126, v127
	v_mfma_f32_32x32x16_bf16 v[84:99], v[4:7], v[136:139], v[84:99]
	v_add_f32_e32 v4, v130, v116
	v_add_f32_e32 v4, v131, v4
	v_cvt_pk_bf16_f32 v150, v128, v129
	v_cvt_pk_bf16_f32 v151, v130, v131
	v_add_f32_e32 v225, v2, v4
	ds_read_b64_tr_b16 v[4:5], v207 offset:29696
	ds_read_b64_tr_b16 v[6:7], v207 offset:30208
	v_mfma_f32_32x32x16_bf16 v[68:83], v[160:163], v[132:135], v[68:83]
	v_exp_f32_e32 v100, v100
	v_exp_f32_e32 v101, v101
	s_add_u32 s98, s6, s36
	s_addc_u32 s99, s7, s37
	v_lshl_add_u64 v[254:255], v[204:205], 0, s[98:99]
	s_lshl_b32 s100, s60, 13
	s_add_i32 s100, s100, s49
	ds_read_b64_tr_b16 v[10:11], v207 offset:26624
	ds_read_b64_tr_b16 v[12:13], v207 offset:27136
	s_waitcnt lgkmcnt(6)
; #define TWAIT_BAR(N) asm volatile("s_waitcnt vmcnt(" #N ") lgkmcnt(0)\n\ts_barrier" ::: "memory")
; #define RESC() do { if constexpr (!NOMAX) if (resc) { asm volatile("s_waitcnt lgkmcnt(0)" ::: "memory"); \
;         _Pragma("unroll") for (int d_ = 0; d_ < 2; ++d_) _Pragma("unroll") for (int r = 0; r < 16; ++r) o[d_][r] *= wsf[crow(r, hi)]; } } while (0)
; #define ROT() do { sl_prev = sl_cur; sl_cur = sl_next; sl_next = (sl_next == 2 * SLOTB) ? 0 : sl_next + SLOTB; } while (0)
; #define RESC() do { if constexpr (!NOMAX) if (resc) { asm volatile("s_waitcnt lgkmcnt(0)" ::: "memory"); \
;         _Pragma("unroll") for (int d_ = 0; d_ < 4; ++d_) _Pragma("unroll") for (int r = 0; r < 16; ++r) o[d_][r] *= wsf[crow(r, hi)]; } } while (0)
; #define ROT() do { sl_prev = sl_cur; sl_cur = sl_next; sl_next = (sl_next == 2) ? 0 : sl_next + 1; } while (0)
; #define RESC() do { if (resc) { asm volatile("s_waitcnt lgkmcnt(0)" ::: "memory"); \
;         _Pragma("unroll") for (int d_ = 0; d_ < 4; ++d_) _Pragma("unroll") for (int r = 0; r < 16; ++r) o[d_][r] *= wsf[crow(r, hi)]; } } while (0)
; template <bool NOMAX>
; __device__ __forceinline__ void diff_unit(const AttnCtx& C, int u, LAS unsigned char* lds) {
;     ...
;     int kk = 1;
;     for (; kk + 7 < n; kk += 2) {
;         STEP(pB0, pB1, pA0, pA1, kk, true, true, true, false);     TWAIT_BAR(3); RESC(); ROT();
;         STEP(pA0, pA1, pB0, pB1, kk + 1, true, true, true, false); TWAIT_BAR(3); RESC(); ROT();
	v_mfma_f32_32x32x16_bf16 v[52:67], v[160:163], v[140:143], v[52:67]
	v_exp_f32_e32 v102, v102
	v_exp_f32_e32 v103, v103
	s_mov_b32 m0, s100
	s_nop 0
	global_load_lds_dwordx4 v[254:255], off
	ds_read_b64_tr_b16 v[116:117], v207 offset:30720
	ds_read_b64_tr_b16 v[118:119], v207 offset:31232
	s_waitcnt lgkmcnt(6)
	v_mfma_f32_32x32x16_bf16 v[68:83], v[156:159], v[14:17], v[68:83]
	v_exp_f32_e32 v104, v104
	v_exp_f32_e32 v105, v105
	ds_read_b64_tr_b16 v[14:15], v207 offset:27648
	ds_read_b64_tr_b16 v[16:17], v207 offset:28160
	s_waitcnt lgkmcnt(6)
	v_mfma_f32_32x32x16_bf16 v[52:67], v[156:159], v[4:7], v[52:67]
	v_exp_f32_e32 v106, v106
	v_exp_f32_e32 v107, v107
	s_add_u32 s98, s6, s38
	s_addc_u32 s99, s7, s39
	v_lshl_add_u64 v[254:255], v[8:9], 0, s[98:99]
	s_lshl_b32 s100, s59, 14
	s_add_i32 s100, s100, s58
	ds_read_b64_tr_b16 v[4:5], v207 offset:31744
	ds_read_b64_tr_b16 v[6:7], v207 offset:32256
	s_waitcnt lgkmcnt(6)
	v_mfma_f32_32x32x16_bf16 v[68:83], v[152:155], v[10:13], v[68:83]
	v_exp_f32_e32 v108, v108
	v_exp_f32_e32 v109, v109
	s_mov_b32 m0, s100
	s_nop 0
	global_load_lds_dwordx4 v[254:255], off
	ds_read_b64_tr_b16 v[10:11], v207 offset:32768
	ds_read_b64_tr_b16 v[12:13], v207 offset:33280
	s_waitcnt lgkmcnt(6)
	v_mfma_f32_32x32x16_bf16 v[52:67], v[152:155], v[116:119], v[52:67]
	v_exp_f32_e32 v110, v110
	v_exp_f32_e32 v111, v111
	ds_read_b64_tr_b16 v[116:117], v207 offset:36864
	ds_read_b64_tr_b16 v[118:119], v207 offset:37376
	s_waitcnt lgkmcnt(6)
	v_mfma_f32_32x32x16_bf16 v[68:83], v[148:151], v[14:17], v[68:83]
	v_exp_f32_e32 v112, v112
	v_exp_f32_e32 v113, v113
	ds_read_b64_tr_b16 v[14:15], v207 offset:33792
	ds_read_b64_tr_b16 v[16:17], v207 offset:34304
	s_waitcnt lgkmcnt(6)
	v_mfma_f32_32x32x16_bf16 v[52:67], v[148:151], v[4:7], v[52:67]
	v_exp_f32_e32 v114, v114
	v_exp_f32_e32 v115, v115
	ds_read_b64_tr_b16 v[4:5], v207 offset:37888
	ds_read_b64_tr_b16 v[6:7], v207 offset:38400
	v_lshl_add_u32 v2, s59, 13, v222
	ds_read_b128 v[192:195], v2
	ds_read_b128 v[184:187], v2 offset:512
	s_waitcnt lgkmcnt(8)
	v_mfma_f32_32x32x16_bf16 v[36:51], v[160:163], v[10:13], v[36:51]
	v_exp_f32_e32 v84, v84
	v_exp_f32_e32 v85, v85
	ds_read_b64_tr_b16 v[10:11], v207 offset:34816
	ds_read_b64_tr_b16 v[12:13], v207 offset:35328
	ds_read_b128 v[188:191], v2 offset:2048
	ds_read_b128 v[180:183], v2 offset:2560
	s_waitcnt lgkmcnt(10)
	v_mfma_f32_32x32x16_bf16 v[20:35], v[160:163], v[116:119], v[20:35]
	v_exp_f32_e32 v86, v86
	v_exp_f32_e32 v87, v87
	ds_read_b64_tr_b16 v[120:121], v207 offset:38912
	ds_read_b64_tr_b16 v[122:123], v207 offset:39424
	ds_read_b128 v[176:179], v2 offset:4096
	ds_read_b128 v[172:175], v2 offset:4608
	s_waitcnt lgkmcnt(12)
	v_mfma_f32_32x32x16_bf16 v[36:51], v[156:159], v[14:17], v[36:51]
	v_exp_f32_e32 v88, v88
	v_exp_f32_e32 v89, v89
	ds_read_b64_tr_b16 v[14:15], v207 offset:35840
	ds_read_b64_tr_b16 v[16:17], v207 offset:36352
	ds_read_b128 v[168:171], v2 offset:6144
	ds_read_b128 v[164:167], v2 offset:6656
	s_waitcnt lgkmcnt(14)
	v_mfma_f32_32x32x16_bf16 v[20:35], v[156:159], v[4:7], v[20:35]
	v_exp_f32_e32 v90, v90
	v_exp_f32_e32 v91, v91
	ds_read_b64_tr_b16 v[4:5], v207 offset:39936
	ds_read_b64_tr_b16 v[6:7], v207 offset:40448
	s_waitcnt lgkmcnt(12)
	v_mfma_f32_32x32x16_bf16 v[36:51], v[152:155], v[10:13], v[36:51]
	v_exp_f32_e32 v92, v92
	v_exp_f32_e32 v93, v93
	s_add_u32 s98, s6, s40
	s_addc_u32 s99, s7, s41
	v_lshl_add_u64 v[254:255], v[8:9], 0, s[98:99]
	s_lshl_b32 s100, s59, 14
	s_add_i32 s100, s100, s58
	s_addk_i32 s100, 0x2000
	ds_read_b128 v[116:119], v219
	s_waitcnt lgkmcnt(9)
	v_mfma_f32_32x32x16_bf16 v[20:35], v[152:155], v[120:123], v[20:35]
	v_exp_f32_e32 v94, v94
	v_exp_f32_e32 v95, v95
	s_mov_b32 m0, s100
	s_nop 0
	global_load_lds_dwordx4 v[254:255], off
	s_waitcnt lgkmcnt(5)
	v_mfma_f32_32x32x16_bf16 v[36:51], v[148:151], v[14:17], v[36:51]
	v_exp_f32_e32 v96, v96
	v_exp_f32_e32 v97, v97
	s_waitcnt lgkmcnt(1)
	v_mfma_f32_32x32x16_bf16 v[20:35], v[148:151], v[4:7], v[20:35]
	v_exp_f32_e32 v98, v98
	v_exp_f32_e32 v99, v99
	s_add_i32 s10, s59, 1
	s_cmp_lg_u32 s59, 2
	s_waitcnt vmcnt(3) lgkmcnt(0)
	s_barrier
	s_cselect_b32 s60, s10, 0
	s_add_i32 s16, s9, 2
	s_add_u32 s6, s6, 0x20000
	v_cmp_ge_u32_e32 vcc, s16, v226
	s_addc_u32 s7, s7, 0
	s_mov_b32 s11, s8
	s_cbranch_vccz .LBB0_463
	s_add_i32 s16, s9, -5
	s_branch .LBB0_467
